# combined + static priority for second wave half + LDS stage-base adds folded into ds_read offsets
# speedup vs baseline: 1.0046x; 1.0000x over previous
.Lprio_skip_120:
	v_add_u32_e32 v226, 0x10000, v212
.LBB0_120:
	s_add_u32 s28, s40, 0xfff80080
	s_addc_u32 s29, s41, -1
	s_add_i32 s54, 0, 0x10000
	s_cmp_eq_u32 s53, 28
	s_cselect_b32 s29, s23, s29
	s_cselect_b32 s28, s22, s28
	s_cselect_b32 s43, s21, s52
	s_cselect_b32 s42, s50, s51
	s_add_i32 s56, 0, 0x14000
	ds_read_b128 v[130:133], v226
	ds_read_b128 v[134:137], v226 offset:1024
	ds_read_b128 v[138:141], v226 offset:2048
	ds_read_b128 v[142:145], v226 offset:3072
	ds_read_b128 v[146:149], v226 offset:16384
	ds_read_b128 v[150:153], v226 offset:17408
	ds_read_b128 v[154:157], v226 offset:18432
	ds_read_b128 v[158:161], v226 offset:19456
	s_add_i32 m0, s24, 0xc000
	ds_read_b128 v[162:165], v213
	ds_read_b128 v[166:169], v213 offset:1024
	ds_read_b128 v[170:173], v213 offset:2048
	ds_read_b128 v[174:177], v213 offset:3072
	ds_read_b128 v[188:191], v213 offset:4096
	ds_read_b128 v[192:195], v213 offset:5120
	ds_read_b128 v[196:199], v213 offset:6144
	ds_read_b128 v[200:203], v213 offset:7168
	global_load_lds_dwordx4 v184, s[40:41]
	s_add_i32 m0, s24, 0xe000
	s_nop 0
	global_load_lds_dwordx4 v186, s[40:41]
	s_waitcnt vmcnt(8)
	s_waitcnt lgkmcnt(0)
	s_barrier
	v_mfma_f32_16x16x32_bf16 v[126:129], v[130:133], v[162:165], v[126:129]
	v_mfma_f32_16x16x32_bf16 v[126:129], v[134:137], v[166:169], v[126:129]
	v_mfma_f32_16x16x32_bf16 v[122:125], v[142:145], v[166:169], v[122:125]
	v_mfma_f32_16x16x32_bf16 v[122:125], v[138:141], v[162:165], v[122:125]
	v_mfma_f32_16x16x32_bf16 v[106:109], v[138:141], v[170:173], v[106:109]
	v_mfma_f32_16x16x32_bf16 v[106:109], v[142:145], v[174:177], v[106:109]
	v_mfma_f32_16x16x32_bf16 v[110:113], v[134:137], v[174:177], v[110:113]
	v_mfma_f32_16x16x32_bf16 v[110:113], v[130:133], v[170:173], v[110:113]
	v_mfma_f32_16x16x32_bf16 v[94:97], v[130:133], v[188:191], v[94:97]
	v_mfma_f32_16x16x32_bf16 v[94:97], v[134:137], v[192:195], v[94:97]
	v_mfma_f32_16x16x32_bf16 v[90:93], v[142:145], v[192:195], v[90:93]
	v_mfma_f32_16x16x32_bf16 v[90:93], v[138:141], v[188:191], v[90:93]
	v_mfma_f32_16x16x32_bf16 v[74:77], v[138:141], v[196:199], v[74:77]
	v_mfma_f32_16x16x32_bf16 v[74:77], v[142:145], v[200:203], v[74:77]
	v_mfma_f32_16x16x32_bf16 v[78:81], v[134:137], v[200:203], v[78:81]
	v_mfma_f32_16x16x32_bf16 v[78:81], v[130:133], v[196:199], v[78:81]
	v_mfma_f32_16x16x32_bf16 v[118:121], v[146:149], v[162:165], v[118:121]
	v_mfma_f32_16x16x32_bf16 v[118:121], v[150:153], v[166:169], v[118:121]
	v_mfma_f32_16x16x32_bf16 v[114:117], v[158:161], v[166:169], v[114:117]
	v_mfma_f32_16x16x32_bf16 v[114:117], v[154:157], v[162:165], v[114:117]
	v_mfma_f32_16x16x32_bf16 v[98:101], v[154:157], v[170:173], v[98:101]
	v_mfma_f32_16x16x32_bf16 v[98:101], v[158:161], v[174:177], v[98:101]
	v_mfma_f32_16x16x32_bf16 v[102:105], v[150:153], v[174:177], v[102:105]
	v_mfma_f32_16x16x32_bf16 v[102:105], v[146:149], v[170:173], v[102:105]
	v_mfma_f32_16x16x32_bf16 v[86:89], v[146:149], v[188:191], v[86:89]
	v_mfma_f32_16x16x32_bf16 v[86:89], v[150:153], v[192:195], v[86:89]
	v_mfma_f32_16x16x32_bf16 v[82:85], v[158:161], v[192:195], v[82:85]
	v_mfma_f32_16x16x32_bf16 v[82:85], v[154:157], v[188:191], v[82:85]
	v_mfma_f32_16x16x32_bf16 v[66:69], v[154:157], v[196:199], v[66:69]
	v_mfma_f32_16x16x32_bf16 v[66:69], v[158:161], v[200:203], v[66:69]
	v_mfma_f32_16x16x32_bf16 v[70:73], v[150:153], v[200:203], v[70:73]
	v_mfma_f32_16x16x32_bf16 v[70:73], v[146:149], v[196:199], v[70:73]
	s_barrier
	s_add_i32 s54, s54, s1
	v_lshl_add_u64 v[204:205], s[42:43], 0, v[32:33]
	s_mov_b32 m0, s54
	ds_read_b128 v[162:165], v213 offset:16384
	ds_read_b128 v[166:169], v213 offset:17408
	ds_read_b128 v[170:173], v213 offset:18432
	ds_read_b128 v[174:177], v213 offset:19456
	ds_read_b128 v[188:191], v213 offset:20480
	ds_read_b128 v[192:195], v213 offset:21504
	ds_read_b128 v[196:199], v213 offset:22528
	ds_read_b128 v[200:203], v213 offset:23552
	global_load_lds_dwordx4 v[204:205], off
	s_add_i32 m0, s54, 0x2000
	s_add_u32 s54, s42, 0x80000
	v_lshl_add_u64 v[206:207], s[42:43], 0, v[182:183]
	s_addc_u32 s55, s43, 0
	s_add_i32 s56, s56, s1
	global_load_lds_dwordx4 v[206:207], off
	s_mov_b32 m0, s56
	v_lshl_add_u64 v[214:215], s[28:29], 0, v[180:181]
	global_load_lds_dwordx4 v32, s[54:55]
	s_add_i32 m0, s56, 0x2000
	s_nop 0
	global_load_lds_dwordx4 v182, s[54:55]
	v_lshl_add_u64 v[208:209], s[28:29], 0, v[178:179]
	s_mov_b32 m0, s24
	s_nop 0
	global_load_lds_dwordx4 v[208:209], off
	s_mov_b32 m0, s25
	s_nop 0
	global_load_lds_dwordx4 v[214:215], off
	s_waitcnt vmcnt(8)
	s_waitcnt lgkmcnt(0)
	s_barrier
	v_mfma_f32_16x16x32_bf16 v[62:65], v[130:133], v[162:165], v[62:65]
	v_mfma_f32_16x16x32_bf16 v[62:65], v[134:137], v[166:169], v[62:65]
	v_mfma_f32_16x16x32_bf16 v[58:61], v[142:145], v[166:169], v[58:61]
	v_mfma_f32_16x16x32_bf16 v[58:61], v[138:141], v[162:165], v[58:61]
	v_mfma_f32_16x16x32_bf16 v[42:45], v[138:141], v[170:173], v[42:45]
	v_mfma_f32_16x16x32_bf16 v[42:45], v[142:145], v[174:177], v[42:45]
	v_mfma_f32_16x16x32_bf16 v[46:49], v[134:137], v[174:177], v[46:49]
	v_mfma_f32_16x16x32_bf16 v[46:49], v[130:133], v[170:173], v[46:49]
	v_mfma_f32_16x16x32_bf16 v[28:31], v[130:133], v[188:191], v[28:31]
	v_mfma_f32_16x16x32_bf16 v[28:31], v[134:137], v[192:195], v[28:31]
	v_mfma_f32_16x16x32_bf16 v[24:27], v[142:145], v[192:195], v[24:27]
	v_mfma_f32_16x16x32_bf16 v[24:27], v[138:141], v[188:191], v[24:27]
	v_mfma_f32_16x16x32_bf16 v[8:11], v[138:141], v[196:199], v[8:11]
	v_mfma_f32_16x16x32_bf16 v[8:11], v[142:145], v[200:203], v[8:11]
	v_mfma_f32_16x16x32_bf16 v[12:15], v[134:137], v[200:203], v[12:15]
	v_mfma_f32_16x16x32_bf16 v[12:15], v[130:133], v[196:199], v[12:15]
	v_mfma_f32_16x16x32_bf16 v[54:57], v[146:149], v[162:165], v[54:57]
	v_mfma_f32_16x16x32_bf16 v[54:57], v[150:153], v[166:169], v[54:57]
	v_mfma_f32_16x16x32_bf16 v[50:53], v[158:161], v[166:169], v[50:53]
	v_mfma_f32_16x16x32_bf16 v[50:53], v[154:157], v[162:165], v[50:53]
	v_mfma_f32_16x16x32_bf16 v[34:37], v[154:157], v[170:173], v[34:37]
	v_mfma_f32_16x16x32_bf16 v[34:37], v[158:161], v[174:177], v[34:37]
	v_mfma_f32_16x16x32_bf16 v[38:41], v[150:153], v[174:177], v[38:41]
	v_mfma_f32_16x16x32_bf16 v[38:41], v[146:149], v[170:173], v[38:41]
	v_mfma_f32_16x16x32_bf16 v[20:23], v[146:149], v[188:191], v[20:23]
	v_mfma_f32_16x16x32_bf16 v[20:23], v[150:153], v[192:195], v[20:23]
	v_mfma_f32_16x16x32_bf16 v[16:19], v[158:161], v[192:195], v[16:19]
	v_mfma_f32_16x16x32_bf16 v[16:19], v[154:157], v[188:191], v[16:19]
	v_mfma_f32_16x16x32_bf16 v[0:3], v[154:157], v[196:199], v[0:3]
	v_mfma_f32_16x16x32_bf16 v[0:3], v[158:161], v[200:203], v[0:3]
	v_mfma_f32_16x16x32_bf16 v[4:7], v[150:153], v[200:203], v[4:7]
	v_mfma_f32_16x16x32_bf16 v[4:7], v[146:149], v[196:199], v[4:7]
	s_barrier
	s_add_i32 s54, 0, 0x18000
	s_add_i32 s55, 0, 0x1c000
	ds_read_b128 v[130:133], v226 offset:32768
	ds_read_b128 v[134:137], v226 offset:33792
	ds_read_b128 v[138:141], v226 offset:34816
	ds_read_b128 v[142:145], v226 offset:35840
	ds_read_b128 v[146:149], v226 offset:49152
	ds_read_b128 v[150:153], v226 offset:50176
	ds_read_b128 v[154:157], v226 offset:51200
	ds_read_b128 v[158:161], v226 offset:52224
	s_add_u32 s28, s28, 0x80000
	s_addc_u32 s29, s29, 0
	s_mov_b32 m0, s33
	ds_read_b128 v[162:165], v213 offset:32768
	ds_read_b128 v[166:169], v213 offset:33792
	ds_read_b128 v[170:173], v213 offset:34816
	ds_read_b128 v[174:177], v213 offset:35840
	ds_read_b128 v[188:191], v213 offset:36864
	ds_read_b128 v[192:195], v213 offset:37888
	ds_read_b128 v[196:199], v213 offset:38912
	ds_read_b128 v[200:203], v213 offset:39936
	global_load_lds_dwordx4 v178, s[28:29]
	s_mov_b32 m0, s36
	s_nop 0
	global_load_lds_dwordx4 v180, s[28:29]
	s_waitcnt vmcnt(8)
	s_waitcnt lgkmcnt(0)
	s_barrier
	v_mfma_f32_16x16x32_bf16 v[126:129], v[130:133], v[162:165], v[126:129]
	v_mfma_f32_16x16x32_bf16 v[126:129], v[134:137], v[166:169], v[126:129]
	v_mfma_f32_16x16x32_bf16 v[122:125], v[142:145], v[166:169], v[122:125]
	v_mfma_f32_16x16x32_bf16 v[122:125], v[138:141], v[162:165], v[122:125]
	v_mfma_f32_16x16x32_bf16 v[106:109], v[138:141], v[170:173], v[106:109]
	v_mfma_f32_16x16x32_bf16 v[106:109], v[142:145], v[174:177], v[106:109]
	v_mfma_f32_16x16x32_bf16 v[110:113], v[134:137], v[174:177], v[110:113]
	v_mfma_f32_16x16x32_bf16 v[110:113], v[130:133], v[170:173], v[110:113]
	v_mfma_f32_16x16x32_bf16 v[94:97], v[130:133], v[188:191], v[94:97]
	v_mfma_f32_16x16x32_bf16 v[94:97], v[134:137], v[192:195], v[94:97]
	v_mfma_f32_16x16x32_bf16 v[90:93], v[142:145], v[192:195], v[90:93]
	v_mfma_f32_16x16x32_bf16 v[90:93], v[138:141], v[188:191], v[90:93]
	v_mfma_f32_16x16x32_bf16 v[74:77], v[138:141], v[196:199], v[74:77]
	v_mfma_f32_16x16x32_bf16 v[74:77], v[142:145], v[200:203], v[74:77]
	v_mfma_f32_16x16x32_bf16 v[78:81], v[134:137], v[200:203], v[78:81]
	v_mfma_f32_16x16x32_bf16 v[78:81], v[130:133], v[196:199], v[78:81]
	v_mfma_f32_16x16x32_bf16 v[118:121], v[146:149], v[162:165], v[118:121]
	v_mfma_f32_16x16x32_bf16 v[118:121], v[150:153], v[166:169], v[118:121]
	v_mfma_f32_16x16x32_bf16 v[114:117], v[158:161], v[166:169], v[114:117]
	v_mfma_f32_16x16x32_bf16 v[114:117], v[154:157], v[162:165], v[114:117]
	v_mfma_f32_16x16x32_bf16 v[98:101], v[154:157], v[170:173], v[98:101]
	v_mfma_f32_16x16x32_bf16 v[98:101], v[158:161], v[174:177], v[98:101]
	v_mfma_f32_16x16x32_bf16 v[102:105], v[150:153], v[174:177], v[102:105]
	v_mfma_f32_16x16x32_bf16 v[102:105], v[146:149], v[170:173], v[102:105]
	v_mfma_f32_16x16x32_bf16 v[86:89], v[146:149], v[188:191], v[86:89]
	v_mfma_f32_16x16x32_bf16 v[86:89], v[150:153], v[192:195], v[86:89]
	v_mfma_f32_16x16x32_bf16 v[82:85], v[158:161], v[192:195], v[82:85]
	v_mfma_f32_16x16x32_bf16 v[82:85], v[154:157], v[188:191], v[82:85]
	v_mfma_f32_16x16x32_bf16 v[66:69], v[154:157], v[196:199], v[66:69]
	v_mfma_f32_16x16x32_bf16 v[66:69], v[158:161], v[200:203], v[66:69]
	v_mfma_f32_16x16x32_bf16 v[70:73], v[150:153], v[200:203], v[70:73]
	v_mfma_f32_16x16x32_bf16 v[70:73], v[146:149], v[196:199], v[70:73]
	s_barrier
	s_add_i32 s28, s54, s1
	v_lshl_add_u64 v[204:205], v[204:205], 0, s[34:35]
	s_mov_b32 m0, s28
	ds_read_b128 v[162:165], v213 offset:49152
	ds_read_b128 v[166:169], v213 offset:50176
	ds_read_b128 v[170:173], v213 offset:51200
	ds_read_b128 v[174:177], v213 offset:52224
	ds_read_b128 v[188:191], v213 offset:53248
	ds_read_b128 v[192:195], v213 offset:54272
	ds_read_b128 v[196:199], v213 offset:55296
	ds_read_b128 v[200:203], v213 offset:56320
	global_load_lds_dwordx4 v[204:205], off
	s_add_i32 m0, s28, 0x2000
	s_add_u32 s28, s42, 0x80080
	v_lshl_add_u64 v[204:205], v[206:207], 0, s[34:35]
	s_addc_u32 s29, s43, 0
	s_add_i32 s42, s55, s1
	global_load_lds_dwordx4 v[204:205], off
	s_mov_b32 m0, s42
	s_nop 0
	global_load_lds_dwordx4 v32, s[28:29]
	s_add_i32 m0, s42, 0x2000
	s_nop 0
	global_load_lds_dwordx4 v182, s[28:29]
	v_lshl_add_u64 v[204:205], v[208:209], 0, s[34:35]
	s_mov_b32 m0, s44
	s_nop 0
	global_load_lds_dwordx4 v[204:205], off
	v_lshl_add_u64 v[204:205], v[214:215], 0, s[34:35]
	s_mov_b32 m0, s45
	s_nop 0
	global_load_lds_dwordx4 v[204:205], off
	s_waitcnt vmcnt(8)
	s_waitcnt lgkmcnt(0)
	s_barrier
	v_mfma_f32_16x16x32_bf16 v[62:65], v[130:133], v[162:165], v[62:65]
	v_mfma_f32_16x16x32_bf16 v[62:65], v[134:137], v[166:169], v[62:65]
	v_mfma_f32_16x16x32_bf16 v[58:61], v[142:145], v[166:169], v[58:61]
	v_mfma_f32_16x16x32_bf16 v[58:61], v[138:141], v[162:165], v[58:61]
	v_mfma_f32_16x16x32_bf16 v[42:45], v[138:141], v[170:173], v[42:45]
	v_mfma_f32_16x16x32_bf16 v[42:45], v[142:145], v[174:177], v[42:45]
	v_mfma_f32_16x16x32_bf16 v[46:49], v[134:137], v[174:177], v[46:49]
	v_mfma_f32_16x16x32_bf16 v[46:49], v[130:133], v[170:173], v[46:49]
	v_mfma_f32_16x16x32_bf16 v[28:31], v[130:133], v[188:191], v[28:31]
	v_mfma_f32_16x16x32_bf16 v[28:31], v[134:137], v[192:195], v[28:31]
	v_mfma_f32_16x16x32_bf16 v[24:27], v[142:145], v[192:195], v[24:27]
	v_mfma_f32_16x16x32_bf16 v[24:27], v[138:141], v[188:191], v[24:27]
	v_mfma_f32_16x16x32_bf16 v[8:11], v[138:141], v[196:199], v[8:11]
	v_mfma_f32_16x16x32_bf16 v[8:11], v[142:145], v[200:203], v[8:11]
	v_mfma_f32_16x16x32_bf16 v[12:15], v[134:137], v[200:203], v[12:15]
	v_mfma_f32_16x16x32_bf16 v[12:15], v[130:133], v[196:199], v[12:15]
	v_mfma_f32_16x16x32_bf16 v[54:57], v[146:149], v[162:165], v[54:57]
	v_mfma_f32_16x16x32_bf16 v[54:57], v[150:153], v[166:169], v[54:57]
	v_mfma_f32_16x16x32_bf16 v[50:53], v[158:161], v[166:169], v[50:53]
	v_mfma_f32_16x16x32_bf16 v[50:53], v[154:157], v[162:165], v[50:53]
	v_mfma_f32_16x16x32_bf16 v[34:37], v[154:157], v[170:173], v[34:37]
	v_mfma_f32_16x16x32_bf16 v[34:37], v[158:161], v[174:177], v[34:37]
	v_mfma_f32_16x16x32_bf16 v[38:41], v[150:153], v[174:177], v[38:41]
	v_mfma_f32_16x16x32_bf16 v[38:41], v[146:149], v[170:173], v[38:41]
	v_mfma_f32_16x16x32_bf16 v[20:23], v[146:149], v[188:191], v[20:23]
	v_mfma_f32_16x16x32_bf16 v[20:23], v[150:153], v[192:195], v[20:23]
	v_mfma_f32_16x16x32_bf16 v[16:19], v[158:161], v[192:195], v[16:19]
	v_mfma_f32_16x16x32_bf16 v[16:19], v[154:157], v[188:191], v[16:19]
	v_mfma_f32_16x16x32_bf16 v[0:3], v[154:157], v[196:199], v[0:3]
	v_mfma_f32_16x16x32_bf16 v[0:3], v[158:161], v[200:203], v[0:3]
	v_mfma_f32_16x16x32_bf16 v[4:7], v[150:153], v[200:203], v[4:7]
	v_mfma_f32_16x16x32_bf16 v[4:7], v[146:149], v[196:199], v[4:7]
	s_barrier
	s_add_i32 s53, s53, 2
	s_add_u32 s40, s40, 0x100
	s_addc_u32 s41, s41, 0
	s_add_u32 s51, s51, 0x100
	s_addc_u32 s52, s52, 0
	s_cmp_gt_u32 s53, 29
	s_cbranch_scc0 .LBB0_120
	s_setprio 0
	s_and_b64 vcc, exec, s[18:19]
	s_cbranch_vccz .LBB0_123
	s_barrier

.Lprio_skip_685:
	v_add_u32_e32 v224, 0x10000, v190
.LBB0_685:
	s_add_u32 s28, s16, s40
	s_addc_u32 s29, s17, s41
	s_add_u32 s28, s28, 0x100
	s_addc_u32 s29, s29, 0
	s_add_u32 s42, s52, s40
	s_addc_u32 s43, s53, s41
	s_add_i32 s56, 0, 0x10000
	s_cmpk_eq_i32 s40, 0xf00
	s_cselect_b32 s29, s39, s29
	s_cselect_b32 s28, s38, s28
	s_cselect_b32 s43, s23, s43
	s_cselect_b32 s42, s54, s42
	s_add_i32 s58, 0, 0x14000
	ds_read_b128 v[134:137], v224
	ds_read_b128 v[138:141], v224 offset:1024
	ds_read_b128 v[142:145], v224 offset:2048
	ds_read_b128 v[146:149], v224 offset:3072
	ds_read_b128 v[150:153], v224 offset:16384
	ds_read_b128 v[154:157], v224 offset:17408
	ds_read_b128 v[158:161], v224 offset:18432
	ds_read_b128 v[162:165], v224 offset:19456
	v_lshl_add_u64 v[212:213], v[130:131], 0, s[40:41]
	s_add_i32 m0, s24, 0xc000
	ds_read_b128 v[166:169], v191
	ds_read_b128 v[180:183], v191 offset:1024
	ds_read_b128 v[184:187], v191 offset:2048
	ds_read_b128 v[192:195], v191 offset:3072
	ds_read_b128 v[196:199], v191 offset:4096
	ds_read_b128 v[200:203], v191 offset:5120
	ds_read_b128 v[204:207], v191 offset:6144
	ds_read_b128 v[208:211], v191 offset:7168
	global_load_lds_dwordx4 v[212:213], off
	v_lshl_add_u64 v[212:213], v[132:133], 0, s[40:41]
	s_add_i32 m0, s24, 0xe000
	s_nop 0
	global_load_lds_dwordx4 v[212:213], off
	s_waitcnt vmcnt(8)
	s_waitcnt lgkmcnt(0)
	s_barrier
	v_mfma_f32_16x16x32_bf16 v[82:85], v[134:137], v[166:169], v[82:85]
	v_mfma_f32_16x16x32_bf16 v[82:85], v[138:141], v[180:183], v[82:85]
	v_mfma_f32_16x16x32_bf16 v[78:81], v[146:149], v[180:183], v[78:81]
	v_mfma_f32_16x16x32_bf16 v[78:81], v[142:145], v[166:169], v[78:81]
	v_mfma_f32_16x16x32_bf16 v[70:73], v[142:145], v[184:187], v[70:73]
	v_mfma_f32_16x16x32_bf16 v[70:73], v[146:149], v[192:195], v[70:73]
	v_mfma_f32_16x16x32_bf16 v[74:77], v[138:141], v[192:195], v[74:77]
	v_mfma_f32_16x16x32_bf16 v[74:77], v[134:137], v[184:187], v[74:77]
	v_mfma_f32_16x16x32_bf16 v[66:69], v[134:137], v[196:199], v[66:69]
	v_mfma_f32_16x16x32_bf16 v[66:69], v[138:141], v[200:203], v[66:69]
	v_mfma_f32_16x16x32_bf16 v[62:65], v[146:149], v[200:203], v[62:65]
	v_mfma_f32_16x16x32_bf16 v[62:65], v[142:145], v[196:199], v[62:65]
	v_mfma_f32_16x16x32_bf16 v[54:57], v[142:145], v[204:207], v[54:57]
	v_mfma_f32_16x16x32_bf16 v[54:57], v[146:149], v[208:211], v[54:57]
	v_mfma_f32_16x16x32_bf16 v[58:61], v[138:141], v[208:211], v[58:61]
	v_mfma_f32_16x16x32_bf16 v[58:61], v[134:137], v[204:207], v[58:61]
	v_mfma_f32_16x16x32_bf16 v[50:53], v[150:153], v[166:169], v[50:53]
	v_mfma_f32_16x16x32_bf16 v[50:53], v[154:157], v[180:183], v[50:53]
	v_mfma_f32_16x16x32_bf16 v[46:49], v[162:165], v[180:183], v[46:49]
	v_mfma_f32_16x16x32_bf16 v[46:49], v[158:161], v[166:169], v[46:49]
	v_mfma_f32_16x16x32_bf16 v[38:41], v[158:161], v[184:187], v[38:41]
	v_mfma_f32_16x16x32_bf16 v[38:41], v[162:165], v[192:195], v[38:41]
	v_mfma_f32_16x16x32_bf16 v[42:45], v[154:157], v[192:195], v[42:45]
	v_mfma_f32_16x16x32_bf16 v[42:45], v[150:153], v[184:187], v[42:45]
	v_mfma_f32_16x16x32_bf16 v[34:37], v[150:153], v[196:199], v[34:37]
	v_mfma_f32_16x16x32_bf16 v[34:37], v[154:157], v[200:203], v[34:37]
	v_mfma_f32_16x16x32_bf16 v[28:31], v[162:165], v[200:203], v[28:31]
	v_mfma_f32_16x16x32_bf16 v[28:31], v[158:161], v[196:199], v[28:31]
	v_mfma_f32_16x16x32_bf16 v[20:23], v[158:161], v[204:207], v[20:23]
	v_mfma_f32_16x16x32_bf16 v[20:23], v[162:165], v[208:211], v[20:23]
	v_mfma_f32_16x16x32_bf16 v[24:27], v[154:157], v[208:211], v[24:27]
	v_mfma_f32_16x16x32_bf16 v[24:27], v[150:153], v[204:207], v[24:27]
	s_barrier
	s_add_i32 s56, s56, s13
	v_lshl_add_u64 v[212:213], s[42:43], 0, v[32:33]
	s_mov_b32 m0, s56
	ds_read_b128 v[166:169], v191 offset:16384
	ds_read_b128 v[180:183], v191 offset:17408
	ds_read_b128 v[184:187], v191 offset:18432
	ds_read_b128 v[192:195], v191 offset:19456
	ds_read_b128 v[196:199], v191 offset:20480
	ds_read_b128 v[200:203], v191 offset:21504
	ds_read_b128 v[204:207], v191 offset:22528
	ds_read_b128 v[208:211], v191 offset:23552
	global_load_lds_dwordx4 v[212:213], off
	s_add_i32 m0, s56, 0x2000
	s_add_u32 s56, s42, 0x80000
	v_lshl_add_u64 v[214:215], s[42:43], 0, v[174:175]
	s_addc_u32 s57, s43, 0
	s_add_i32 s58, s58, s13
	global_load_lds_dwordx4 v[214:215], off
	s_mov_b32 m0, s58
	v_lshl_add_u64 v[220:221], s[28:29], 0, v[172:173]
	global_load_lds_dwordx4 v32, s[56:57]
	s_add_i32 m0, s58, 0x2000
	s_nop 0
	global_load_lds_dwordx4 v174, s[56:57]
	v_lshl_add_u64 v[216:217], s[28:29], 0, v[170:171]
	s_mov_b32 m0, s24
	s_nop 0
	global_load_lds_dwordx4 v[216:217], off
	s_mov_b32 m0, s25
	s_nop 0
	global_load_lds_dwordx4 v[220:221], off
	s_waitcnt vmcnt(8)
	s_waitcnt lgkmcnt(0)
	s_barrier
	v_mfma_f32_16x16x32_bf16 v[16:19], v[134:137], v[166:169], v[16:19]
	v_mfma_f32_16x16x32_bf16 v[16:19], v[138:141], v[180:183], v[16:19]
	v_mfma_f32_16x16x32_bf16 v[12:15], v[146:149], v[180:183], v[12:15]
	v_mfma_f32_16x16x32_bf16 v[12:15], v[142:145], v[166:169], v[12:15]
	v_mfma_f32_16x16x32_bf16 v[4:7], v[142:145], v[184:187], v[4:7]
	v_mfma_f32_16x16x32_bf16 v[4:7], v[146:149], v[192:195], v[4:7]
	v_mfma_f32_16x16x32_bf16 v[8:11], v[138:141], v[192:195], v[8:11]
	v_mfma_f32_16x16x32_bf16 v[8:11], v[134:137], v[184:187], v[8:11]
	v_mfma_f32_16x16x32_bf16 v[0:3], v[134:137], v[196:199], v[0:3]
	v_mfma_f32_16x16x32_bf16 v[0:3], v[138:141], v[200:203], v[0:3]
	v_mfma_f32_16x16x32_bf16 v[86:89], v[146:149], v[200:203], v[86:89]
	v_mfma_f32_16x16x32_bf16 v[86:89], v[142:145], v[196:199], v[86:89]
	v_mfma_f32_16x16x32_bf16 v[94:97], v[142:145], v[204:207], v[94:97]
	v_mfma_f32_16x16x32_bf16 v[94:97], v[146:149], v[208:211], v[94:97]
	v_mfma_f32_16x16x32_bf16 v[90:93], v[138:141], v[208:211], v[90:93]
	v_mfma_f32_16x16x32_bf16 v[90:93], v[134:137], v[204:207], v[90:93]
	v_mfma_f32_16x16x32_bf16 v[98:101], v[150:153], v[166:169], v[98:101]
	v_mfma_f32_16x16x32_bf16 v[98:101], v[154:157], v[180:183], v[98:101]
	v_mfma_f32_16x16x32_bf16 v[102:105], v[162:165], v[180:183], v[102:105]
	v_mfma_f32_16x16x32_bf16 v[102:105], v[158:161], v[166:169], v[102:105]
	v_mfma_f32_16x16x32_bf16 v[110:113], v[158:161], v[184:187], v[110:113]
	v_mfma_f32_16x16x32_bf16 v[110:113], v[162:165], v[192:195], v[110:113]
	v_mfma_f32_16x16x32_bf16 v[106:109], v[154:157], v[192:195], v[106:109]
	v_mfma_f32_16x16x32_bf16 v[106:109], v[150:153], v[184:187], v[106:109]
	v_mfma_f32_16x16x32_bf16 v[114:117], v[150:153], v[196:199], v[114:117]
	v_mfma_f32_16x16x32_bf16 v[114:117], v[154:157], v[200:203], v[114:117]
	v_mfma_f32_16x16x32_bf16 v[118:121], v[162:165], v[200:203], v[118:121]
	v_mfma_f32_16x16x32_bf16 v[118:121], v[158:161], v[196:199], v[118:121]
	v_mfma_f32_16x16x32_bf16 v[126:129], v[158:161], v[204:207], v[126:129]
	v_mfma_f32_16x16x32_bf16 v[126:129], v[162:165], v[208:211], v[126:129]
	v_mfma_f32_16x16x32_bf16 v[122:125], v[154:157], v[208:211], v[122:125]
	v_mfma_f32_16x16x32_bf16 v[122:125], v[150:153], v[204:207], v[122:125]
	s_barrier
	s_add_i32 s56, 0, 0x18000
	s_add_i32 s57, 0, 0x1c000
	ds_read_b128 v[134:137], v224 offset:32768
	ds_read_b128 v[138:141], v224 offset:33792
	ds_read_b128 v[142:145], v224 offset:34816
	ds_read_b128 v[146:149], v224 offset:35840
	ds_read_b128 v[150:153], v224 offset:49152
	ds_read_b128 v[154:157], v224 offset:50176
	ds_read_b128 v[158:161], v224 offset:51200
	ds_read_b128 v[162:165], v224 offset:52224
	s_add_u32 s28, s28, 0x80000
	s_addc_u32 s29, s29, 0
	s_mov_b32 m0, s33
	ds_read_b128 v[166:169], v191 offset:32768
	ds_read_b128 v[180:183], v191 offset:33792
	ds_read_b128 v[184:187], v191 offset:34816
	ds_read_b128 v[192:195], v191 offset:35840
	ds_read_b128 v[196:199], v191 offset:36864
	ds_read_b128 v[200:203], v191 offset:37888
	ds_read_b128 v[204:207], v191 offset:38912
	ds_read_b128 v[208:211], v191 offset:39936
	global_load_lds_dwordx4 v170, s[28:29]
	s_mov_b32 m0, s36
	s_nop 0
	global_load_lds_dwordx4 v172, s[28:29]
	s_waitcnt vmcnt(8)
	s_waitcnt lgkmcnt(0)
	s_barrier
	v_mfma_f32_16x16x32_bf16 v[82:85], v[134:137], v[166:169], v[82:85]
	v_mfma_f32_16x16x32_bf16 v[82:85], v[138:141], v[180:183], v[82:85]
	v_mfma_f32_16x16x32_bf16 v[78:81], v[146:149], v[180:183], v[78:81]
	v_mfma_f32_16x16x32_bf16 v[78:81], v[142:145], v[166:169], v[78:81]
	v_mfma_f32_16x16x32_bf16 v[70:73], v[142:145], v[184:187], v[70:73]
	v_mfma_f32_16x16x32_bf16 v[70:73], v[146:149], v[192:195], v[70:73]
	v_mfma_f32_16x16x32_bf16 v[74:77], v[138:141], v[192:195], v[74:77]
	v_mfma_f32_16x16x32_bf16 v[74:77], v[134:137], v[184:187], v[74:77]
	v_mfma_f32_16x16x32_bf16 v[66:69], v[134:137], v[196:199], v[66:69]
	v_mfma_f32_16x16x32_bf16 v[66:69], v[138:141], v[200:203], v[66:69]
	v_mfma_f32_16x16x32_bf16 v[62:65], v[146:149], v[200:203], v[62:65]
	v_mfma_f32_16x16x32_bf16 v[62:65], v[142:145], v[196:199], v[62:65]
	v_mfma_f32_16x16x32_bf16 v[54:57], v[142:145], v[204:207], v[54:57]
	v_mfma_f32_16x16x32_bf16 v[54:57], v[146:149], v[208:211], v[54:57]
	v_mfma_f32_16x16x32_bf16 v[58:61], v[138:141], v[208:211], v[58:61]
	v_mfma_f32_16x16x32_bf16 v[58:61], v[134:137], v[204:207], v[58:61]
	v_mfma_f32_16x16x32_bf16 v[50:53], v[150:153], v[166:169], v[50:53]
	v_mfma_f32_16x16x32_bf16 v[50:53], v[154:157], v[180:183], v[50:53]
	v_mfma_f32_16x16x32_bf16 v[46:49], v[162:165], v[180:183], v[46:49]
	v_mfma_f32_16x16x32_bf16 v[46:49], v[158:161], v[166:169], v[46:49]
	v_mfma_f32_16x16x32_bf16 v[38:41], v[158:161], v[184:187], v[38:41]
	v_mfma_f32_16x16x32_bf16 v[38:41], v[162:165], v[192:195], v[38:41]
	v_mfma_f32_16x16x32_bf16 v[42:45], v[154:157], v[192:195], v[42:45]
	v_mfma_f32_16x16x32_bf16 v[42:45], v[150:153], v[184:187], v[42:45]
	v_mfma_f32_16x16x32_bf16 v[34:37], v[150:153], v[196:199], v[34:37]
	v_mfma_f32_16x16x32_bf16 v[34:37], v[154:157], v[200:203], v[34:37]
	v_mfma_f32_16x16x32_bf16 v[28:31], v[162:165], v[200:203], v[28:31]
	v_mfma_f32_16x16x32_bf16 v[28:31], v[158:161], v[196:199], v[28:31]
	v_mfma_f32_16x16x32_bf16 v[20:23], v[158:161], v[204:207], v[20:23]
	v_mfma_f32_16x16x32_bf16 v[20:23], v[162:165], v[208:211], v[20:23]
	v_mfma_f32_16x16x32_bf16 v[24:27], v[154:157], v[208:211], v[24:27]
	v_mfma_f32_16x16x32_bf16 v[24:27], v[150:153], v[204:207], v[24:27]
	s_barrier
	s_add_i32 s28, s56, s13
	v_lshl_add_u64 v[212:213], v[212:213], 0, s[34:35]
	s_mov_b32 m0, s28
	ds_read_b128 v[166:169], v191 offset:49152
	ds_read_b128 v[180:183], v191 offset:50176
	ds_read_b128 v[184:187], v191 offset:51200
	ds_read_b128 v[192:195], v191 offset:52224
	ds_read_b128 v[196:199], v191 offset:53248
	ds_read_b128 v[200:203], v191 offset:54272
	ds_read_b128 v[204:207], v191 offset:55296
	ds_read_b128 v[208:211], v191 offset:56320
	global_load_lds_dwordx4 v[212:213], off
	s_add_i32 m0, s28, 0x2000
	s_add_u32 s28, s42, 0x80080
	v_lshl_add_u64 v[212:213], v[214:215], 0, s[34:35]
	s_addc_u32 s29, s43, 0
	s_add_i32 s42, s57, s13
	global_load_lds_dwordx4 v[212:213], off
	s_mov_b32 m0, s42
	s_nop 0
	global_load_lds_dwordx4 v32, s[28:29]
	s_add_i32 m0, s42, 0x2000
	s_nop 0
	global_load_lds_dwordx4 v174, s[28:29]
	v_lshl_add_u64 v[212:213], v[216:217], 0, s[34:35]
	s_mov_b32 m0, s45
	s_nop 0
	global_load_lds_dwordx4 v[212:213], off
	v_lshl_add_u64 v[212:213], v[220:221], 0, s[34:35]
	s_mov_b32 m0, s46
	s_nop 0
	global_load_lds_dwordx4 v[212:213], off
	s_waitcnt vmcnt(8)
	s_waitcnt lgkmcnt(0)
	s_barrier
	v_mfma_f32_16x16x32_bf16 v[16:19], v[134:137], v[166:169], v[16:19]
	v_mfma_f32_16x16x32_bf16 v[16:19], v[138:141], v[180:183], v[16:19]
	v_mfma_f32_16x16x32_bf16 v[12:15], v[146:149], v[180:183], v[12:15]
	v_mfma_f32_16x16x32_bf16 v[12:15], v[142:145], v[166:169], v[12:15]
	v_mfma_f32_16x16x32_bf16 v[4:7], v[142:145], v[184:187], v[4:7]
	v_mfma_f32_16x16x32_bf16 v[4:7], v[146:149], v[192:195], v[4:7]
	v_mfma_f32_16x16x32_bf16 v[8:11], v[138:141], v[192:195], v[8:11]
	v_mfma_f32_16x16x32_bf16 v[8:11], v[134:137], v[184:187], v[8:11]
	v_mfma_f32_16x16x32_bf16 v[0:3], v[134:137], v[196:199], v[0:3]
	v_mfma_f32_16x16x32_bf16 v[0:3], v[138:141], v[200:203], v[0:3]
	v_mfma_f32_16x16x32_bf16 v[86:89], v[146:149], v[200:203], v[86:89]
	v_mfma_f32_16x16x32_bf16 v[86:89], v[142:145], v[196:199], v[86:89]
	v_mfma_f32_16x16x32_bf16 v[94:97], v[142:145], v[204:207], v[94:97]
	v_mfma_f32_16x16x32_bf16 v[94:97], v[146:149], v[208:211], v[94:97]
	v_mfma_f32_16x16x32_bf16 v[90:93], v[138:141], v[208:211], v[90:93]
	v_mfma_f32_16x16x32_bf16 v[90:93], v[134:137], v[204:207], v[90:93]
	v_mfma_f32_16x16x32_bf16 v[98:101], v[150:153], v[166:169], v[98:101]
	v_mfma_f32_16x16x32_bf16 v[98:101], v[154:157], v[180:183], v[98:101]
	v_mfma_f32_16x16x32_bf16 v[102:105], v[162:165], v[180:183], v[102:105]
	v_mfma_f32_16x16x32_bf16 v[102:105], v[158:161], v[166:169], v[102:105]
	v_mfma_f32_16x16x32_bf16 v[110:113], v[158:161], v[184:187], v[110:113]
	v_mfma_f32_16x16x32_bf16 v[110:113], v[162:165], v[192:195], v[110:113]
	v_mfma_f32_16x16x32_bf16 v[106:109], v[154:157], v[192:195], v[106:109]
	v_mfma_f32_16x16x32_bf16 v[106:109], v[150:153], v[184:187], v[106:109]
	v_mfma_f32_16x16x32_bf16 v[114:117], v[150:153], v[196:199], v[114:117]
	v_mfma_f32_16x16x32_bf16 v[114:117], v[154:157], v[200:203], v[114:117]
	v_mfma_f32_16x16x32_bf16 v[118:121], v[162:165], v[200:203], v[118:121]
	v_mfma_f32_16x16x32_bf16 v[118:121], v[158:161], v[196:199], v[118:121]
	v_mfma_f32_16x16x32_bf16 v[126:129], v[158:161], v[204:207], v[126:129]
	v_mfma_f32_16x16x32_bf16 v[126:129], v[162:165], v[208:211], v[126:129]
	v_mfma_f32_16x16x32_bf16 v[122:125], v[154:157], v[208:211], v[122:125]
	v_mfma_f32_16x16x32_bf16 v[122:125], v[150:153], v[204:207], v[122:125]
	s_barrier
	s_add_i32 s55, s55, 2
	s_add_u32 s40, s40, 0x100
	s_addc_u32 s41, s41, 0
	s_cmp_gt_u32 s55, 29
	s_cbranch_scc0 .LBB0_685
	s_setprio 0
	s_and_b64 vcc, exec, s[18:19]
	s_cbranch_vccz .LBB0_688
	s_barrier

.Lprio_skip_755:
	v_add_u32_e32 v248, 0x10000, v242
.LBB0_755:
	s_add_u32 s6, s4, 0x100
	s_addc_u32 s7, s5, 0
	s_add_i32 s52, 0, 0x10000
	s_cmpk_eq_i32 s51, 0x54
	s_cselect_b32 s29, s23, s7
	s_cselect_b32 s28, s22, s6
	s_cselect_b32 s31, s27, s50
	s_cselect_b32 s30, s26, s33
	s_add_i32 s53, 0, 0x14000
	ds_read_b128 v[130:133], v248
	ds_read_b128 v[134:137], v248 offset:1024
	ds_read_b128 v[138:141], v248 offset:2048
	ds_read_b128 v[142:145], v248 offset:3072
	ds_read_b128 v[146:149], v248 offset:16384
	ds_read_b128 v[150:153], v248 offset:17408
	ds_read_b128 v[154:157], v248 offset:18432
	ds_read_b128 v[158:161], v248 offset:19456
	s_add_i32 m0, s36, 0xc000
	ds_read_b128 v[162:165], v243
	ds_read_b128 v[166:169], v243 offset:1024
	ds_read_b128 v[170:173], v243 offset:2048
	ds_read_b128 v[174:177], v243 offset:3072
	ds_read_b128 v[178:181], v243 offset:4096
	ds_read_b128 v[182:185], v243 offset:5120
	ds_read_b128 v[186:189], v243 offset:6144
	ds_read_b128 v[190:193], v243 offset:7168
	global_load_lds_dwordx4 v202, s[4:5]
	s_add_i32 m0, s36, 0xe000
	s_nop 0
	global_load_lds_dwordx4 v204, s[4:5]
	s_waitcnt vmcnt(8)
	s_waitcnt lgkmcnt(0)
	s_barrier
	v_mfma_f32_16x16x32_bf16 v[126:129], v[130:133], v[162:165], v[126:129]
	v_mfma_f32_16x16x32_bf16 v[126:129], v[134:137], v[166:169], v[126:129]
	v_mfma_f32_16x16x32_bf16 v[122:125], v[142:145], v[166:169], v[122:125]
	v_mfma_f32_16x16x32_bf16 v[122:125], v[138:141], v[162:165], v[122:125]
	v_mfma_f32_16x16x32_bf16 v[106:109], v[138:141], v[170:173], v[106:109]
	v_mfma_f32_16x16x32_bf16 v[106:109], v[142:145], v[174:177], v[106:109]
	v_mfma_f32_16x16x32_bf16 v[110:113], v[134:137], v[174:177], v[110:113]
	v_mfma_f32_16x16x32_bf16 v[110:113], v[130:133], v[170:173], v[110:113]
	v_mfma_f32_16x16x32_bf16 v[94:97], v[130:133], v[178:181], v[94:97]
	v_mfma_f32_16x16x32_bf16 v[94:97], v[134:137], v[182:185], v[94:97]
	v_mfma_f32_16x16x32_bf16 v[90:93], v[142:145], v[182:185], v[90:93]
	v_mfma_f32_16x16x32_bf16 v[90:93], v[138:141], v[178:181], v[90:93]
	v_mfma_f32_16x16x32_bf16 v[74:77], v[138:141], v[186:189], v[74:77]
	v_mfma_f32_16x16x32_bf16 v[74:77], v[142:145], v[190:193], v[74:77]
	v_mfma_f32_16x16x32_bf16 v[78:81], v[134:137], v[190:193], v[78:81]
	v_mfma_f32_16x16x32_bf16 v[78:81], v[130:133], v[186:189], v[78:81]
	v_mfma_f32_16x16x32_bf16 v[118:121], v[146:149], v[162:165], v[118:121]
	v_mfma_f32_16x16x32_bf16 v[118:121], v[150:153], v[166:169], v[118:121]
	v_mfma_f32_16x16x32_bf16 v[114:117], v[158:161], v[166:169], v[114:117]
	v_mfma_f32_16x16x32_bf16 v[114:117], v[154:157], v[162:165], v[114:117]
	v_mfma_f32_16x16x32_bf16 v[98:101], v[154:157], v[170:173], v[98:101]
	v_mfma_f32_16x16x32_bf16 v[98:101], v[158:161], v[174:177], v[98:101]
	v_mfma_f32_16x16x32_bf16 v[102:105], v[150:153], v[174:177], v[102:105]
	v_mfma_f32_16x16x32_bf16 v[102:105], v[146:149], v[170:173], v[102:105]
	v_mfma_f32_16x16x32_bf16 v[86:89], v[146:149], v[178:181], v[86:89]
	v_mfma_f32_16x16x32_bf16 v[86:89], v[150:153], v[182:185], v[86:89]
	v_mfma_f32_16x16x32_bf16 v[82:85], v[158:161], v[182:185], v[82:85]
	v_mfma_f32_16x16x32_bf16 v[82:85], v[154:157], v[178:181], v[82:85]
	v_mfma_f32_16x16x32_bf16 v[66:69], v[154:157], v[186:189], v[66:69]
	v_mfma_f32_16x16x32_bf16 v[66:69], v[158:161], v[190:193], v[66:69]
	v_mfma_f32_16x16x32_bf16 v[70:73], v[150:153], v[190:193], v[70:73]
	v_mfma_f32_16x16x32_bf16 v[70:73], v[146:149], v[186:189], v[70:73]
	s_barrier
	s_add_i32 s4, s52, s1
	v_lshl_add_u64 v[194:195], s[30:31], 0, v[32:33]
	s_mov_b32 m0, s4
	ds_read_b128 v[162:165], v243 offset:16384
	ds_read_b128 v[166:169], v243 offset:17408
	ds_read_b128 v[170:173], v243 offset:18432
	ds_read_b128 v[174:177], v243 offset:19456
	ds_read_b128 v[178:181], v243 offset:20480
	ds_read_b128 v[182:185], v243 offset:21504
	ds_read_b128 v[186:189], v243 offset:22528
	ds_read_b128 v[190:193], v243 offset:23552
	global_load_lds_dwordx4 v[194:195], off
	s_add_i32 m0, s4, 0x2000
	s_add_u32 s4, s30, 0x160000
	v_lshl_add_u64 v[206:207], s[30:31], 0, v[200:201]
	s_addc_u32 s5, s31, 0
	s_add_i32 s52, s53, s1
	global_load_lds_dwordx4 v[206:207], off
	s_mov_b32 m0, s52
	v_lshl_add_u64 v[210:211], s[28:29], 0, v[198:199]
	global_load_lds_dwordx4 v32, s[4:5]
	s_add_i32 m0, s52, 0x2000
	s_nop 0
	global_load_lds_dwordx4 v200, s[4:5]
	v_lshl_add_u64 v[208:209], s[28:29], 0, v[196:197]
	s_mov_b32 m0, s36
	s_nop 0
	global_load_lds_dwordx4 v[208:209], off
	s_mov_b32 m0, s38
	s_nop 0
	global_load_lds_dwordx4 v[210:211], off
	s_waitcnt vmcnt(8)
	s_waitcnt lgkmcnt(0)
	s_barrier
	v_mfma_f32_16x16x32_bf16 v[62:65], v[130:133], v[162:165], v[62:65]
	v_mfma_f32_16x16x32_bf16 v[62:65], v[134:137], v[166:169], v[62:65]
	v_mfma_f32_16x16x32_bf16 v[58:61], v[142:145], v[166:169], v[58:61]
	v_mfma_f32_16x16x32_bf16 v[58:61], v[138:141], v[162:165], v[58:61]
	v_mfma_f32_16x16x32_bf16 v[42:45], v[138:141], v[170:173], v[42:45]
	v_mfma_f32_16x16x32_bf16 v[42:45], v[142:145], v[174:177], v[42:45]
	v_mfma_f32_16x16x32_bf16 v[46:49], v[134:137], v[174:177], v[46:49]
	v_mfma_f32_16x16x32_bf16 v[46:49], v[130:133], v[170:173], v[46:49]
	v_mfma_f32_16x16x32_bf16 v[28:31], v[130:133], v[178:181], v[28:31]
	v_mfma_f32_16x16x32_bf16 v[28:31], v[134:137], v[182:185], v[28:31]
	v_mfma_f32_16x16x32_bf16 v[24:27], v[142:145], v[182:185], v[24:27]
	v_mfma_f32_16x16x32_bf16 v[24:27], v[138:141], v[178:181], v[24:27]
	v_mfma_f32_16x16x32_bf16 v[8:11], v[138:141], v[186:189], v[8:11]
	v_mfma_f32_16x16x32_bf16 v[8:11], v[142:145], v[190:193], v[8:11]
	v_mfma_f32_16x16x32_bf16 v[12:15], v[134:137], v[190:193], v[12:15]
	v_mfma_f32_16x16x32_bf16 v[12:15], v[130:133], v[186:189], v[12:15]
	v_mfma_f32_16x16x32_bf16 v[54:57], v[146:149], v[162:165], v[54:57]
	v_mfma_f32_16x16x32_bf16 v[54:57], v[150:153], v[166:169], v[54:57]
	v_mfma_f32_16x16x32_bf16 v[50:53], v[158:161], v[166:169], v[50:53]
	v_mfma_f32_16x16x32_bf16 v[50:53], v[154:157], v[162:165], v[50:53]
	v_mfma_f32_16x16x32_bf16 v[34:37], v[154:157], v[170:173], v[34:37]
	v_mfma_f32_16x16x32_bf16 v[34:37], v[158:161], v[174:177], v[34:37]
	v_mfma_f32_16x16x32_bf16 v[38:41], v[150:153], v[174:177], v[38:41]
	v_mfma_f32_16x16x32_bf16 v[38:41], v[146:149], v[170:173], v[38:41]
	v_mfma_f32_16x16x32_bf16 v[20:23], v[146:149], v[178:181], v[20:23]
	v_mfma_f32_16x16x32_bf16 v[20:23], v[150:153], v[182:185], v[20:23]
	v_mfma_f32_16x16x32_bf16 v[16:19], v[158:161], v[182:185], v[16:19]
	v_mfma_f32_16x16x32_bf16 v[16:19], v[154:157], v[178:181], v[16:19]
	v_mfma_f32_16x16x32_bf16 v[0:3], v[154:157], v[186:189], v[0:3]
	v_mfma_f32_16x16x32_bf16 v[0:3], v[158:161], v[190:193], v[0:3]
	v_mfma_f32_16x16x32_bf16 v[4:7], v[150:153], v[190:193], v[4:7]
	v_mfma_f32_16x16x32_bf16 v[4:7], v[146:149], v[186:189], v[4:7]
	s_barrier
	s_add_i32 s52, 0, 0x18000
	s_add_i32 s53, 0, 0x1c000
	ds_read_b128 v[130:133], v248 offset:32768
	ds_read_b128 v[134:137], v248 offset:33792
	ds_read_b128 v[138:141], v248 offset:34816
	ds_read_b128 v[142:145], v248 offset:35840
	ds_read_b128 v[146:149], v248 offset:49152
	ds_read_b128 v[150:153], v248 offset:50176
	ds_read_b128 v[154:157], v248 offset:51200
	ds_read_b128 v[158:161], v248 offset:52224
	s_add_u32 s4, s28, 0x160000
	s_addc_u32 s5, s29, 0
	s_mov_b32 m0, s39
	ds_read_b128 v[162:165], v243 offset:32768
	ds_read_b128 v[166:169], v243 offset:33792
	ds_read_b128 v[170:173], v243 offset:34816
	ds_read_b128 v[174:177], v243 offset:35840
	ds_read_b128 v[178:181], v243 offset:36864
	ds_read_b128 v[182:185], v243 offset:37888
	ds_read_b128 v[186:189], v243 offset:38912
	ds_read_b128 v[190:193], v243 offset:39936
	global_load_lds_dwordx4 v196, s[4:5]
	s_mov_b32 m0, s42
	s_nop 0
	global_load_lds_dwordx4 v198, s[4:5]
	s_waitcnt vmcnt(8)
	s_waitcnt lgkmcnt(0)
	s_barrier
	v_mfma_f32_16x16x32_bf16 v[126:129], v[130:133], v[162:165], v[126:129]
	v_mfma_f32_16x16x32_bf16 v[126:129], v[134:137], v[166:169], v[126:129]
	v_mfma_f32_16x16x32_bf16 v[122:125], v[142:145], v[166:169], v[122:125]
	v_mfma_f32_16x16x32_bf16 v[122:125], v[138:141], v[162:165], v[122:125]
	v_mfma_f32_16x16x32_bf16 v[106:109], v[138:141], v[170:173], v[106:109]
	v_mfma_f32_16x16x32_bf16 v[106:109], v[142:145], v[174:177], v[106:109]
	v_mfma_f32_16x16x32_bf16 v[110:113], v[134:137], v[174:177], v[110:113]
	v_mfma_f32_16x16x32_bf16 v[110:113], v[130:133], v[170:173], v[110:113]
	v_mfma_f32_16x16x32_bf16 v[94:97], v[130:133], v[178:181], v[94:97]
	v_mfma_f32_16x16x32_bf16 v[94:97], v[134:137], v[182:185], v[94:97]
	v_mfma_f32_16x16x32_bf16 v[90:93], v[142:145], v[182:185], v[90:93]
	v_mfma_f32_16x16x32_bf16 v[90:93], v[138:141], v[178:181], v[90:93]
	v_mfma_f32_16x16x32_bf16 v[74:77], v[138:141], v[186:189], v[74:77]
	v_mfma_f32_16x16x32_bf16 v[74:77], v[142:145], v[190:193], v[74:77]
	v_mfma_f32_16x16x32_bf16 v[78:81], v[134:137], v[190:193], v[78:81]
	v_mfma_f32_16x16x32_bf16 v[78:81], v[130:133], v[186:189], v[78:81]
	v_mfma_f32_16x16x32_bf16 v[118:121], v[146:149], v[162:165], v[118:121]
	v_mfma_f32_16x16x32_bf16 v[118:121], v[150:153], v[166:169], v[118:121]
	v_mfma_f32_16x16x32_bf16 v[114:117], v[158:161], v[166:169], v[114:117]
	v_mfma_f32_16x16x32_bf16 v[114:117], v[154:157], v[162:165], v[114:117]
	v_mfma_f32_16x16x32_bf16 v[98:101], v[154:157], v[170:173], v[98:101]
	v_mfma_f32_16x16x32_bf16 v[98:101], v[158:161], v[174:177], v[98:101]
	v_mfma_f32_16x16x32_bf16 v[102:105], v[150:153], v[174:177], v[102:105]
	v_mfma_f32_16x16x32_bf16 v[102:105], v[146:149], v[170:173], v[102:105]
	v_mfma_f32_16x16x32_bf16 v[86:89], v[146:149], v[178:181], v[86:89]
	v_mfma_f32_16x16x32_bf16 v[86:89], v[150:153], v[182:185], v[86:89]
	v_mfma_f32_16x16x32_bf16 v[82:85], v[158:161], v[182:185], v[82:85]
	v_mfma_f32_16x16x32_bf16 v[82:85], v[154:157], v[178:181], v[82:85]
	v_mfma_f32_16x16x32_bf16 v[66:69], v[154:157], v[186:189], v[66:69]
	v_mfma_f32_16x16x32_bf16 v[66:69], v[158:161], v[190:193], v[66:69]
	v_mfma_f32_16x16x32_bf16 v[70:73], v[150:153], v[190:193], v[70:73]
	v_mfma_f32_16x16x32_bf16 v[70:73], v[146:149], v[186:189], v[70:73]
	s_barrier
	s_add_i32 s4, s52, s1
	v_lshl_add_u64 v[194:195], v[194:195], 0, s[34:35]
	s_mov_b32 m0, s4
	ds_read_b128 v[162:165], v243 offset:49152
	ds_read_b128 v[166:169], v243 offset:50176
	ds_read_b128 v[170:173], v243 offset:51200
	ds_read_b128 v[174:177], v243 offset:52224
	ds_read_b128 v[178:181], v243 offset:53248
	ds_read_b128 v[182:185], v243 offset:54272
	ds_read_b128 v[186:189], v243 offset:55296
	ds_read_b128 v[190:193], v243 offset:56320
	global_load_lds_dwordx4 v[194:195], off
	s_add_i32 m0, s4, 0x2000
	s_add_u32 s4, s30, 0x160080
	v_lshl_add_u64 v[194:195], v[206:207], 0, s[34:35]
	s_addc_u32 s5, s31, 0
	s_add_i32 s28, s53, s1
	global_load_lds_dwordx4 v[194:195], off
	s_mov_b32 m0, s28
	s_nop 0
	global_load_lds_dwordx4 v32, s[4:5]
	s_add_i32 m0, s28, 0x2000
	s_nop 0
	global_load_lds_dwordx4 v200, s[4:5]
	v_lshl_add_u64 v[194:195], v[208:209], 0, s[34:35]
	s_mov_b32 m0, s44
	s_nop 0
	global_load_lds_dwordx4 v[194:195], off
	v_lshl_add_u64 v[194:195], v[210:211], 0, s[34:35]
	s_mov_b32 m0, s45
	s_nop 0
	global_load_lds_dwordx4 v[194:195], off
	s_waitcnt vmcnt(8)
	s_waitcnt lgkmcnt(0)
	s_barrier
	v_mfma_f32_16x16x32_bf16 v[62:65], v[130:133], v[162:165], v[62:65]
	v_mfma_f32_16x16x32_bf16 v[62:65], v[134:137], v[166:169], v[62:65]
	v_mfma_f32_16x16x32_bf16 v[58:61], v[142:145], v[166:169], v[58:61]
	v_mfma_f32_16x16x32_bf16 v[58:61], v[138:141], v[162:165], v[58:61]
	v_mfma_f32_16x16x32_bf16 v[42:45], v[138:141], v[170:173], v[42:45]
	v_mfma_f32_16x16x32_bf16 v[42:45], v[142:145], v[174:177], v[42:45]
	v_mfma_f32_16x16x32_bf16 v[46:49], v[134:137], v[174:177], v[46:49]
	v_mfma_f32_16x16x32_bf16 v[46:49], v[130:133], v[170:173], v[46:49]
	v_mfma_f32_16x16x32_bf16 v[28:31], v[130:133], v[178:181], v[28:31]
	v_mfma_f32_16x16x32_bf16 v[28:31], v[134:137], v[182:185], v[28:31]
	v_mfma_f32_16x16x32_bf16 v[24:27], v[142:145], v[182:185], v[24:27]
	v_mfma_f32_16x16x32_bf16 v[24:27], v[138:141], v[178:181], v[24:27]
	v_mfma_f32_16x16x32_bf16 v[8:11], v[138:141], v[186:189], v[8:11]
	v_mfma_f32_16x16x32_bf16 v[8:11], v[142:145], v[190:193], v[8:11]
	v_mfma_f32_16x16x32_bf16 v[12:15], v[134:137], v[190:193], v[12:15]
	v_mfma_f32_16x16x32_bf16 v[12:15], v[130:133], v[186:189], v[12:15]
	v_mfma_f32_16x16x32_bf16 v[54:57], v[146:149], v[162:165], v[54:57]
	v_mfma_f32_16x16x32_bf16 v[54:57], v[150:153], v[166:169], v[54:57]
	v_mfma_f32_16x16x32_bf16 v[50:53], v[158:161], v[166:169], v[50:53]
	v_mfma_f32_16x16x32_bf16 v[50:53], v[154:157], v[162:165], v[50:53]
	v_mfma_f32_16x16x32_bf16 v[34:37], v[154:157], v[170:173], v[34:37]
	v_mfma_f32_16x16x32_bf16 v[34:37], v[158:161], v[174:177], v[34:37]
	v_mfma_f32_16x16x32_bf16 v[38:41], v[150:153], v[174:177], v[38:41]
	v_mfma_f32_16x16x32_bf16 v[38:41], v[146:149], v[170:173], v[38:41]
	v_mfma_f32_16x16x32_bf16 v[20:23], v[146:149], v[178:181], v[20:23]
	v_mfma_f32_16x16x32_bf16 v[20:23], v[150:153], v[182:185], v[20:23]
	v_mfma_f32_16x16x32_bf16 v[16:19], v[158:161], v[182:185], v[16:19]
	v_mfma_f32_16x16x32_bf16 v[16:19], v[154:157], v[178:181], v[16:19]
	v_mfma_f32_16x16x32_bf16 v[0:3], v[154:157], v[186:189], v[0:3]
	v_mfma_f32_16x16x32_bf16 v[0:3], v[158:161], v[190:193], v[0:3]
	v_mfma_f32_16x16x32_bf16 v[4:7], v[150:153], v[190:193], v[4:7]
	v_mfma_f32_16x16x32_bf16 v[4:7], v[146:149], v[186:189], v[4:7]
	s_barrier
	s_add_i32 s51, s51, 2
	s_add_u32 s33, s33, 0x100
	s_addc_u32 s50, s50, 0
	s_cmpk_gt_u32 s51, 0x55
	s_mov_b64 s[4:5], s[6:7]
	s_cbranch_scc0 .LBB0_755
	s_setprio 0
	s_and_b64 vcc, exec, s[18:19]
	s_cbranch_vccz .LBB0_758
	s_barrier

.Lprio_skip_888:
	v_add_u32_e32 v224, 0x10000, v178
.LBB0_888:
	s_add_u32 s38, s16, s30
	s_addc_u32 s39, s17, s31
	s_add_u32 s38, s38, 0x100
	s_addc_u32 s39, s39, 0
	s_add_u32 s54, s50, s30
	s_addc_u32 s55, s51, s31
	s_add_i32 s56, 0, 0x10000
	s_cmpk_eq_i32 s30, 0xf00
	s_cselect_b32 s41, s29, s39
	s_cselect_b32 s40, s28, s38
	s_cselect_b32 s39, s21, s55
	s_cselect_b32 s38, s52, s54
	s_add_i32 s57, 0, 0x14000
	ds_read_b128 v[134:137], v224
	ds_read_b128 v[138:141], v224 offset:1024
	ds_read_b128 v[142:145], v224 offset:2048
	ds_read_b128 v[146:149], v224 offset:3072
	ds_read_b128 v[150:153], v224 offset:16384
	ds_read_b128 v[154:157], v224 offset:17408
	ds_read_b128 v[158:161], v224 offset:18432
	ds_read_b128 v[172:175], v224 offset:19456
	v_lshl_add_u64 v[212:213], v[130:131], 0, s[30:31]
	s_add_i32 m0, s24, 0xc000
	ds_read_b128 v[180:183], v179
	ds_read_b128 v[184:187], v179 offset:1024
	ds_read_b128 v[188:191], v179 offset:2048
	ds_read_b128 v[192:195], v179 offset:3072
	ds_read_b128 v[196:199], v179 offset:4096
	ds_read_b128 v[200:203], v179 offset:5120
	ds_read_b128 v[204:207], v179 offset:6144
	ds_read_b128 v[208:211], v179 offset:7168
	global_load_lds_dwordx4 v[212:213], off
	v_lshl_add_u64 v[212:213], v[132:133], 0, s[30:31]
	s_add_i32 m0, s24, 0xe000
	s_nop 0
	global_load_lds_dwordx4 v[212:213], off
	s_waitcnt vmcnt(8)
	s_waitcnt lgkmcnt(0)
	s_barrier
	v_mfma_f32_16x16x32_bf16 v[82:85], v[134:137], v[180:183], v[82:85]
	v_mfma_f32_16x16x32_bf16 v[82:85], v[138:141], v[184:187], v[82:85]
	v_mfma_f32_16x16x32_bf16 v[78:81], v[146:149], v[184:187], v[78:81]
	v_mfma_f32_16x16x32_bf16 v[78:81], v[142:145], v[180:183], v[78:81]
	v_mfma_f32_16x16x32_bf16 v[70:73], v[142:145], v[188:191], v[70:73]
	v_mfma_f32_16x16x32_bf16 v[70:73], v[146:149], v[192:195], v[70:73]
	v_mfma_f32_16x16x32_bf16 v[74:77], v[138:141], v[192:195], v[74:77]
	v_mfma_f32_16x16x32_bf16 v[74:77], v[134:137], v[188:191], v[74:77]
	v_mfma_f32_16x16x32_bf16 v[66:69], v[134:137], v[196:199], v[66:69]
	v_mfma_f32_16x16x32_bf16 v[66:69], v[138:141], v[200:203], v[66:69]
	v_mfma_f32_16x16x32_bf16 v[62:65], v[146:149], v[200:203], v[62:65]
	v_mfma_f32_16x16x32_bf16 v[62:65], v[142:145], v[196:199], v[62:65]
	v_mfma_f32_16x16x32_bf16 v[54:57], v[142:145], v[204:207], v[54:57]
	v_mfma_f32_16x16x32_bf16 v[54:57], v[146:149], v[208:211], v[54:57]
	v_mfma_f32_16x16x32_bf16 v[58:61], v[138:141], v[208:211], v[58:61]
	v_mfma_f32_16x16x32_bf16 v[58:61], v[134:137], v[204:207], v[58:61]
	v_mfma_f32_16x16x32_bf16 v[50:53], v[150:153], v[180:183], v[50:53]
	v_mfma_f32_16x16x32_bf16 v[50:53], v[154:157], v[184:187], v[50:53]
	v_mfma_f32_16x16x32_bf16 v[46:49], v[172:175], v[184:187], v[46:49]
	v_mfma_f32_16x16x32_bf16 v[46:49], v[158:161], v[180:183], v[46:49]
	v_mfma_f32_16x16x32_bf16 v[38:41], v[158:161], v[188:191], v[38:41]
	v_mfma_f32_16x16x32_bf16 v[38:41], v[172:175], v[192:195], v[38:41]
	v_mfma_f32_16x16x32_bf16 v[42:45], v[154:157], v[192:195], v[42:45]
	v_mfma_f32_16x16x32_bf16 v[42:45], v[150:153], v[188:191], v[42:45]
	v_mfma_f32_16x16x32_bf16 v[34:37], v[150:153], v[196:199], v[34:37]
	v_mfma_f32_16x16x32_bf16 v[34:37], v[154:157], v[200:203], v[34:37]
	v_mfma_f32_16x16x32_bf16 v[28:31], v[172:175], v[200:203], v[28:31]
	v_mfma_f32_16x16x32_bf16 v[28:31], v[158:161], v[196:199], v[28:31]
	v_mfma_f32_16x16x32_bf16 v[20:23], v[158:161], v[204:207], v[20:23]
	v_mfma_f32_16x16x32_bf16 v[20:23], v[172:175], v[208:211], v[20:23]
	v_mfma_f32_16x16x32_bf16 v[24:27], v[154:157], v[208:211], v[24:27]
	v_mfma_f32_16x16x32_bf16 v[24:27], v[150:153], v[204:207], v[24:27]
	s_barrier
	s_add_i32 s54, s56, s13
	v_lshl_add_u64 v[212:213], s[38:39], 0, v[32:33]
	s_mov_b32 m0, s54
	ds_read_b128 v[180:183], v179 offset:16384
	ds_read_b128 v[184:187], v179 offset:17408
	ds_read_b128 v[188:191], v179 offset:18432
	ds_read_b128 v[192:195], v179 offset:19456
	ds_read_b128 v[196:199], v179 offset:20480
	ds_read_b128 v[200:203], v179 offset:21504
	ds_read_b128 v[204:207], v179 offset:22528
	ds_read_b128 v[208:211], v179 offset:23552
	global_load_lds_dwordx4 v[212:213], off
	s_add_i32 m0, s54, 0x2000
	s_add_u32 s54, s38, 0x80000
	v_lshl_add_u64 v[214:215], s[38:39], 0, v[166:167]
	s_addc_u32 s55, s39, 0
	s_add_i32 s56, s57, s13
	global_load_lds_dwordx4 v[214:215], off
	s_mov_b32 m0, s56
	v_lshl_add_u64 v[220:221], s[40:41], 0, v[164:165]
	global_load_lds_dwordx4 v32, s[54:55]
	s_add_i32 m0, s56, 0x2000
	s_nop 0
	global_load_lds_dwordx4 v166, s[54:55]
	v_lshl_add_u64 v[216:217], s[40:41], 0, v[162:163]
	s_mov_b32 m0, s24
	s_nop 0
	global_load_lds_dwordx4 v[216:217], off
	s_mov_b32 m0, s25
	s_nop 0
	global_load_lds_dwordx4 v[220:221], off
	s_waitcnt vmcnt(8)
	s_waitcnt lgkmcnt(0)
	s_barrier
	v_mfma_f32_16x16x32_bf16 v[16:19], v[134:137], v[180:183], v[16:19]
	v_mfma_f32_16x16x32_bf16 v[16:19], v[138:141], v[184:187], v[16:19]
	v_mfma_f32_16x16x32_bf16 v[12:15], v[146:149], v[184:187], v[12:15]
	v_mfma_f32_16x16x32_bf16 v[12:15], v[142:145], v[180:183], v[12:15]
	v_mfma_f32_16x16x32_bf16 v[4:7], v[142:145], v[188:191], v[4:7]
	v_mfma_f32_16x16x32_bf16 v[4:7], v[146:149], v[192:195], v[4:7]
	v_mfma_f32_16x16x32_bf16 v[8:11], v[138:141], v[192:195], v[8:11]
	v_mfma_f32_16x16x32_bf16 v[8:11], v[134:137], v[188:191], v[8:11]
	v_mfma_f32_16x16x32_bf16 v[0:3], v[134:137], v[196:199], v[0:3]
	v_mfma_f32_16x16x32_bf16 v[0:3], v[138:141], v[200:203], v[0:3]
	v_mfma_f32_16x16x32_bf16 v[86:89], v[146:149], v[200:203], v[86:89]
	v_mfma_f32_16x16x32_bf16 v[86:89], v[142:145], v[196:199], v[86:89]
	v_mfma_f32_16x16x32_bf16 v[94:97], v[142:145], v[204:207], v[94:97]
	v_mfma_f32_16x16x32_bf16 v[94:97], v[146:149], v[208:211], v[94:97]
	v_mfma_f32_16x16x32_bf16 v[90:93], v[138:141], v[208:211], v[90:93]
	v_mfma_f32_16x16x32_bf16 v[90:93], v[134:137], v[204:207], v[90:93]
	v_mfma_f32_16x16x32_bf16 v[98:101], v[150:153], v[180:183], v[98:101]
	v_mfma_f32_16x16x32_bf16 v[98:101], v[154:157], v[184:187], v[98:101]
	v_mfma_f32_16x16x32_bf16 v[102:105], v[172:175], v[184:187], v[102:105]
	v_mfma_f32_16x16x32_bf16 v[102:105], v[158:161], v[180:183], v[102:105]
	v_mfma_f32_16x16x32_bf16 v[110:113], v[158:161], v[188:191], v[110:113]
	v_mfma_f32_16x16x32_bf16 v[110:113], v[172:175], v[192:195], v[110:113]
	v_mfma_f32_16x16x32_bf16 v[106:109], v[154:157], v[192:195], v[106:109]
	v_mfma_f32_16x16x32_bf16 v[106:109], v[150:153], v[188:191], v[106:109]
	v_mfma_f32_16x16x32_bf16 v[114:117], v[150:153], v[196:199], v[114:117]
	v_mfma_f32_16x16x32_bf16 v[114:117], v[154:157], v[200:203], v[114:117]
	v_mfma_f32_16x16x32_bf16 v[118:121], v[172:175], v[200:203], v[118:121]
	v_mfma_f32_16x16x32_bf16 v[118:121], v[158:161], v[196:199], v[118:121]
	v_mfma_f32_16x16x32_bf16 v[126:129], v[158:161], v[204:207], v[126:129]
	v_mfma_f32_16x16x32_bf16 v[126:129], v[172:175], v[208:211], v[126:129]
	v_mfma_f32_16x16x32_bf16 v[122:125], v[154:157], v[208:211], v[122:125]
	v_mfma_f32_16x16x32_bf16 v[122:125], v[150:153], v[204:207], v[122:125]
	s_barrier
	s_add_i32 s54, 0, 0x18000
	s_add_i32 s55, 0, 0x1c000
	ds_read_b128 v[134:137], v224 offset:32768
	ds_read_b128 v[138:141], v224 offset:33792
	ds_read_b128 v[142:145], v224 offset:34816
	ds_read_b128 v[146:149], v224 offset:35840
	ds_read_b128 v[150:153], v224 offset:49152
	ds_read_b128 v[154:157], v224 offset:50176
	ds_read_b128 v[158:161], v224 offset:51200
	ds_read_b128 v[172:175], v224 offset:52224
	s_add_u32 s40, s40, 0x80000
	s_addc_u32 s41, s41, 0
	s_mov_b32 m0, s33
	ds_read_b128 v[180:183], v179 offset:32768
	ds_read_b128 v[184:187], v179 offset:33792
	ds_read_b128 v[188:191], v179 offset:34816
	ds_read_b128 v[192:195], v179 offset:35840
	ds_read_b128 v[196:199], v179 offset:36864
	ds_read_b128 v[200:203], v179 offset:37888
	ds_read_b128 v[204:207], v179 offset:38912
	ds_read_b128 v[208:211], v179 offset:39936
	global_load_lds_dwordx4 v162, s[40:41]
	s_mov_b32 m0, s36
	s_nop 0
	global_load_lds_dwordx4 v164, s[40:41]
	s_waitcnt vmcnt(8)
	s_waitcnt lgkmcnt(0)
	s_barrier
	v_mfma_f32_16x16x32_bf16 v[82:85], v[134:137], v[180:183], v[82:85]
	v_mfma_f32_16x16x32_bf16 v[82:85], v[138:141], v[184:187], v[82:85]
	v_mfma_f32_16x16x32_bf16 v[78:81], v[146:149], v[184:187], v[78:81]
	v_mfma_f32_16x16x32_bf16 v[78:81], v[142:145], v[180:183], v[78:81]
	v_mfma_f32_16x16x32_bf16 v[70:73], v[142:145], v[188:191], v[70:73]
	v_mfma_f32_16x16x32_bf16 v[70:73], v[146:149], v[192:195], v[70:73]
	v_mfma_f32_16x16x32_bf16 v[74:77], v[138:141], v[192:195], v[74:77]
	v_mfma_f32_16x16x32_bf16 v[74:77], v[134:137], v[188:191], v[74:77]
	v_mfma_f32_16x16x32_bf16 v[66:69], v[134:137], v[196:199], v[66:69]
	v_mfma_f32_16x16x32_bf16 v[66:69], v[138:141], v[200:203], v[66:69]
	v_mfma_f32_16x16x32_bf16 v[62:65], v[146:149], v[200:203], v[62:65]
	v_mfma_f32_16x16x32_bf16 v[62:65], v[142:145], v[196:199], v[62:65]
	v_mfma_f32_16x16x32_bf16 v[54:57], v[142:145], v[204:207], v[54:57]
	v_mfma_f32_16x16x32_bf16 v[54:57], v[146:149], v[208:211], v[54:57]
	v_mfma_f32_16x16x32_bf16 v[58:61], v[138:141], v[208:211], v[58:61]
	v_mfma_f32_16x16x32_bf16 v[58:61], v[134:137], v[204:207], v[58:61]
	v_mfma_f32_16x16x32_bf16 v[50:53], v[150:153], v[180:183], v[50:53]
	v_mfma_f32_16x16x32_bf16 v[50:53], v[154:157], v[184:187], v[50:53]
	v_mfma_f32_16x16x32_bf16 v[46:49], v[172:175], v[184:187], v[46:49]
	v_mfma_f32_16x16x32_bf16 v[46:49], v[158:161], v[180:183], v[46:49]
	v_mfma_f32_16x16x32_bf16 v[38:41], v[158:161], v[188:191], v[38:41]
	v_mfma_f32_16x16x32_bf16 v[38:41], v[172:175], v[192:195], v[38:41]
	v_mfma_f32_16x16x32_bf16 v[42:45], v[154:157], v[192:195], v[42:45]
	v_mfma_f32_16x16x32_bf16 v[42:45], v[150:153], v[188:191], v[42:45]
	v_mfma_f32_16x16x32_bf16 v[34:37], v[150:153], v[196:199], v[34:37]
	v_mfma_f32_16x16x32_bf16 v[34:37], v[154:157], v[200:203], v[34:37]
	v_mfma_f32_16x16x32_bf16 v[28:31], v[172:175], v[200:203], v[28:31]
	v_mfma_f32_16x16x32_bf16 v[28:31], v[158:161], v[196:199], v[28:31]
	v_mfma_f32_16x16x32_bf16 v[20:23], v[158:161], v[204:207], v[20:23]
	v_mfma_f32_16x16x32_bf16 v[20:23], v[172:175], v[208:211], v[20:23]
	v_mfma_f32_16x16x32_bf16 v[24:27], v[154:157], v[208:211], v[24:27]
	v_mfma_f32_16x16x32_bf16 v[24:27], v[150:153], v[204:207], v[24:27]
	s_barrier
	s_add_i32 s40, s54, s13
	v_lshl_add_u64 v[212:213], v[212:213], 0, s[34:35]
	s_mov_b32 m0, s40
	ds_read_b128 v[180:183], v179 offset:49152
	ds_read_b128 v[184:187], v179 offset:50176
	ds_read_b128 v[188:191], v179 offset:51200
	ds_read_b128 v[192:195], v179 offset:52224
	ds_read_b128 v[196:199], v179 offset:53248
	ds_read_b128 v[200:203], v179 offset:54272
	ds_read_b128 v[204:207], v179 offset:55296
	ds_read_b128 v[208:211], v179 offset:56320
	global_load_lds_dwordx4 v[212:213], off
	s_add_i32 m0, s40, 0x2000
	s_add_u32 s38, s38, 0x80080
	v_lshl_add_u64 v[212:213], v[214:215], 0, s[34:35]
	s_addc_u32 s39, s39, 0
	s_add_i32 s40, s55, s13
	global_load_lds_dwordx4 v[212:213], off
	s_mov_b32 m0, s40
	s_nop 0
	global_load_lds_dwordx4 v32, s[38:39]
	s_add_i32 m0, s40, 0x2000
	s_nop 0
	global_load_lds_dwordx4 v166, s[38:39]
	v_lshl_add_u64 v[212:213], v[216:217], 0, s[34:35]
	s_mov_b32 m0, s43
	s_nop 0
	global_load_lds_dwordx4 v[212:213], off
	v_lshl_add_u64 v[212:213], v[220:221], 0, s[34:35]
	s_mov_b32 m0, s44
	s_nop 0
	global_load_lds_dwordx4 v[212:213], off
	s_waitcnt vmcnt(8)
	s_waitcnt lgkmcnt(0)
	s_barrier
	v_mfma_f32_16x16x32_bf16 v[16:19], v[134:137], v[180:183], v[16:19]
	v_mfma_f32_16x16x32_bf16 v[16:19], v[138:141], v[184:187], v[16:19]
	v_mfma_f32_16x16x32_bf16 v[12:15], v[146:149], v[184:187], v[12:15]
	v_mfma_f32_16x16x32_bf16 v[12:15], v[142:145], v[180:183], v[12:15]
	v_mfma_f32_16x16x32_bf16 v[4:7], v[142:145], v[188:191], v[4:7]
	v_mfma_f32_16x16x32_bf16 v[4:7], v[146:149], v[192:195], v[4:7]
	v_mfma_f32_16x16x32_bf16 v[8:11], v[138:141], v[192:195], v[8:11]
	v_mfma_f32_16x16x32_bf16 v[8:11], v[134:137], v[188:191], v[8:11]
	v_mfma_f32_16x16x32_bf16 v[0:3], v[134:137], v[196:199], v[0:3]
	v_mfma_f32_16x16x32_bf16 v[0:3], v[138:141], v[200:203], v[0:3]
	v_mfma_f32_16x16x32_bf16 v[86:89], v[146:149], v[200:203], v[86:89]
	v_mfma_f32_16x16x32_bf16 v[86:89], v[142:145], v[196:199], v[86:89]
	v_mfma_f32_16x16x32_bf16 v[94:97], v[142:145], v[204:207], v[94:97]
	v_mfma_f32_16x16x32_bf16 v[94:97], v[146:149], v[208:211], v[94:97]
	v_mfma_f32_16x16x32_bf16 v[90:93], v[138:141], v[208:211], v[90:93]
	v_mfma_f32_16x16x32_bf16 v[90:93], v[134:137], v[204:207], v[90:93]
	v_mfma_f32_16x16x32_bf16 v[98:101], v[150:153], v[180:183], v[98:101]
	v_mfma_f32_16x16x32_bf16 v[98:101], v[154:157], v[184:187], v[98:101]
	v_mfma_f32_16x16x32_bf16 v[102:105], v[172:175], v[184:187], v[102:105]
	v_mfma_f32_16x16x32_bf16 v[102:105], v[158:161], v[180:183], v[102:105]
	v_mfma_f32_16x16x32_bf16 v[110:113], v[158:161], v[188:191], v[110:113]
	v_mfma_f32_16x16x32_bf16 v[110:113], v[172:175], v[192:195], v[110:113]
	v_mfma_f32_16x16x32_bf16 v[106:109], v[154:157], v[192:195], v[106:109]
	v_mfma_f32_16x16x32_bf16 v[106:109], v[150:153], v[188:191], v[106:109]
	v_mfma_f32_16x16x32_bf16 v[114:117], v[150:153], v[196:199], v[114:117]
	v_mfma_f32_16x16x32_bf16 v[114:117], v[154:157], v[200:203], v[114:117]
	v_mfma_f32_16x16x32_bf16 v[118:121], v[172:175], v[200:203], v[118:121]
	v_mfma_f32_16x16x32_bf16 v[118:121], v[158:161], v[196:199], v[118:121]
	v_mfma_f32_16x16x32_bf16 v[126:129], v[158:161], v[204:207], v[126:129]
	v_mfma_f32_16x16x32_bf16 v[126:129], v[172:175], v[208:211], v[126:129]
	v_mfma_f32_16x16x32_bf16 v[122:125], v[154:157], v[208:211], v[122:125]
	v_mfma_f32_16x16x32_bf16 v[122:125], v[150:153], v[204:207], v[122:125]
	s_barrier
	s_add_i32 s53, s53, 2
	s_add_u32 s30, s30, 0x100
	s_addc_u32 s31, s31, 0
	s_cmp_gt_u32 s53, 29
	s_cbranch_scc0 .LBB0_888
	s_setprio 0
	s_and_b64 vcc, exec, s[18:19]
	s_cbranch_vccz .LBB0_891
	s_barrier
